# unrolled attention loops: rare paths (rescale, bias, tail waits, extra DMA piece, skip and P.V-only trips) moved out of line so the steady-state trip has no taken branch; address calc hoisted before t
# speedup vs baseline: 1.0200x; 1.0103x over previous
.LBB0_228:
	s_add_i32 s86, s9, 1
	s_and_b64 vcc, exec, s[16:17]
	s_cbranch_vccnz .LA1_top
.LB1_top:
	s_cmp_ge_u32 s65, s66
	s_cbranch_scc1 .Lnod_b1
	s_add_i32 s4, s65, 1
	s_cmp_ge_u32 s4, s66
	s_cbranch_scc1 .Lvo_b1
	s_mov_b32 m0, s32
	s_nop 0
	global_load_lds_dwordx4 v128, s[80:81]
	s_add_i32 m0, m0, 0x2000
	s_nop 0
	global_load_lds_dwordx4 v129, s[80:81]
	s_add_i32 m0, s32, 0x12800
	s_nop 0
	global_load_lds_dwordx4 v130, s[80:81]
	s_add_i32 m0, m0, 0x2000
	s_nop 0
	global_load_lds_dwordx4 v131, s[80:81]
	s_cmp_eq_u32 s56, 0
	s_cbranch_scc1 .LkX_b1
	s_add_i32 m0, s32, 0x16400
	s_nop 0
	global_load_lds_dwordx4 v132, s[80:81]

.Lnod_b1:
	s_cmp_gt_i32 s65, s86
	s_cbranch_scc1 .LB1_skip
	v_max_f32_e32 v176, v96, v80
	v_max3_f32 v177, v81, v98, v82
	v_max3_f32 v176, v176, v97, v99
	v_max3_f32 v177, v177, v100, v84
	v_max3_f32 v176, v176, v83, v101
	v_max3_f32 v177, v177, v102, v86
	v_max3_f32 v176, v176, v85, v103
	v_max3_f32 v177, v177, v104, v88
	v_max3_f32 v176, v176, v87, v105
	v_max3_f32 v177, v177, v106, v90
	v_max3_f32 v176, v176, v89, v107
	v_max3_f32 v177, v177, v108, v92
	v_max3_f32 v176, v176, v91, v109
	v_max3_f32 v177, v177, v110, v94
	v_max3_f32 v176, v176, v93, v111
	v_max3_f32 v176, v176, v95, v177
	v_mov_b32_e32 v177, v176
	s_nop 1
	v_permlane32_swap_b32_e32 v176, v177
	v_max_f32_e32 v176, v176, v177
	v_cmp_lt_f32_e32 vcc, 0x41000000, v176
	s_cbranch_vccnz .Lrs_b1
.Latt_b1_exp:
	v_exp_f32_e32 v96, v96
	v_exp_f32_e32 v97, v97
	v_exp_f32_e32 v176, v80
	v_exp_f32_e32 v177, v81
	v_exp_f32_e32 v98, v98
	v_exp_f32_e32 v99, v99
	v_exp_f32_e32 v178, v82
	v_exp_f32_e32 v179, v83
	v_exp_f32_e32 v100, v100
	v_exp_f32_e32 v101, v101
	v_exp_f32_e32 v180, v84
	v_exp_f32_e32 v181, v85
	v_exp_f32_e32 v102, v102
	v_exp_f32_e32 v103, v103
	v_exp_f32_e32 v182, v86
	v_exp_f32_e32 v183, v87
	v_exp_f32_e32 v104, v104
	v_exp_f32_e32 v105, v105
	v_exp_f32_e32 v184, v88
	v_exp_f32_e32 v185, v89
	v_exp_f32_e32 v106, v106
	v_exp_f32_e32 v107, v107
	v_exp_f32_e32 v186, v90
	v_exp_f32_e32 v187, v91
	v_exp_f32_e32 v108, v108
	v_exp_f32_e32 v109, v109
	v_exp_f32_e32 v188, v92
	v_exp_f32_e32 v189, v93
	v_exp_f32_e32 v110, v110
	v_exp_f32_e32 v111, v111
	v_exp_f32_e32 v190, v94
	v_exp_f32_e32 v191, v95
	v_cvt_pk_bf16_f32 v80, v96, v97
	v_cvt_pk_bf16_f32 v81, v98, v99
	v_cvt_pk_bf16_f32 v82, v100, v101
	v_cvt_pk_bf16_f32 v83, v102, v103
	v_cvt_pk_bf16_f32 v84, v104, v105
	v_cvt_pk_bf16_f32 v85, v106, v107
	v_cvt_pk_bf16_f32 v86, v108, v109
	v_cvt_pk_bf16_f32 v87, v110, v111
	v_cvt_pk_bf16_f32 v88, v176, v177
	v_cvt_pk_bf16_f32 v89, v178, v179
	v_cvt_pk_bf16_f32 v90, v180, v181
	v_cvt_pk_bf16_f32 v91, v182, v183
	v_cvt_pk_bf16_f32 v92, v184, v185
	v_cvt_pk_bf16_f32 v93, v186, v187
	v_cvt_pk_bf16_f32 v94, v188, v189
	v_cvt_pk_bf16_f32 v95, v190, v191
	v_pk_add_f32 v[96:97], v[96:97], v[100:101]
	v_pk_add_f32 v[98:99], v[98:99], v[102:103]
	v_pk_add_f32 v[176:177], v[176:177], v[180:181]
	v_pk_add_f32 v[178:179], v[178:179], v[182:183]
	v_pk_add_f32 v[96:97], v[96:97], v[104:105]
	v_pk_add_f32 v[98:99], v[98:99], v[106:107]
	v_pk_add_f32 v[176:177], v[176:177], v[184:185]
	v_pk_add_f32 v[178:179], v[178:179], v[186:187]
	v_pk_add_f32 v[96:97], v[96:97], v[108:109]
	v_pk_add_f32 v[98:99], v[98:99], v[110:111]
	v_pk_add_f32 v[176:177], v[176:177], v[188:189]
	v_pk_add_f32 v[178:179], v[178:179], v[190:191]
	v_pk_add_f32 v[96:97], v[96:97], v[98:99]
	v_pk_add_f32 v[176:177], v[176:177], v[178:179]
	s_nop 0
	v_pk_add_f32 v[96:97], v[96:97], v[176:177]
	s_nop 0
	v_add_f32_e32 v96, v96, v97
	v_add_f32_e32 v172, v172, v96
	s_cmp_ge_i32 s65, s86
	s_cbranch_scc1 .LB1_pvonly
	v_add_u32_e32 v205, 0x5000, v165
	v_add_u32_e32 v206, 0x20400, v192
	s_add_i32 s4, s65, 1
	s_cmp_lt_u32 s4, s66
	s_cbranch_scc0 .Lw0_b1
	s_waitcnt vmcnt(5) lgkmcnt(0)
.Lwd_b1:
	s_barrier
	ds_read_b64_tr_b16 v[96:97], v205 offset:34816
	ds_read_b64_tr_b16 v[98:99], v205 offset:37376
	ds_read_b64_tr_b16 v[100:101], v205 offset:39936
	ds_read_b64_tr_b16 v[102:103], v205 offset:42496
	ds_read_b64_tr_b16 v[104:105], v205 offset:45056
	ds_read_b64_tr_b16 v[106:107], v205 offset:47616
	ds_read_b64_tr_b16 v[108:109], v205 offset:50176
	ds_read_b64_tr_b16 v[110:111], v205 offset:52736
	ds_read_b64_tr_b16 v[176:177], v205 offset:34880
	ds_read_b64_tr_b16 v[178:179], v205 offset:37440
	ds_read_b64_tr_b16 v[180:181], v205 offset:40000
	ds_read_b64_tr_b16 v[182:183], v205 offset:42560
	ds_read_b64_tr_b16 v[184:185], v205 offset:45120
	ds_read_b64_tr_b16 v[186:187], v205 offset:47680
	s_setprio 1
	s_waitcnt lgkmcnt(12)
	v_mfma_f32_32x32x16_bf16 v[32:47], v[96:99], v[80:83], v[32:47]
	ds_read_b64_tr_b16 v[96:97], v205 offset:50240
	ds_read_b64_tr_b16 v[98:99], v205 offset:52800
	s_waitcnt lgkmcnt(12)
	v_mfma_f32_32x32x16_bf16 v[32:47], v[100:103], v[84:87], v[32:47]
	ds_read_b64_tr_b16 v[100:101], v205 offset:34944
	ds_read_b64_tr_b16 v[102:103], v205 offset:37504
	s_waitcnt lgkmcnt(12)
	v_mfma_f32_32x32x16_bf16 v[32:47], v[104:107], v[88:91], v[32:47]
	ds_read_b64_tr_b16 v[104:105], v205 offset:40064
	ds_read_b64_tr_b16 v[106:107], v205 offset:42624
	s_waitcnt lgkmcnt(12)
	v_mfma_f32_32x32x16_bf16 v[32:47], v[108:111], v[92:95], v[32:47]
	ds_read_b64_tr_b16 v[108:109], v205 offset:45184
	ds_read_b64_tr_b16 v[110:111], v205 offset:47744
	s_waitcnt lgkmcnt(12)
	v_mfma_f32_32x32x16_bf16 v[16:31], v[176:179], v[80:83], v[16:31]
	ds_read_b64_tr_b16 v[176:177], v205 offset:50304
	ds_read_b64_tr_b16 v[178:179], v205 offset:52864
	s_waitcnt lgkmcnt(12)
	v_mfma_f32_32x32x16_bf16 v[16:31], v[180:183], v[84:87], v[16:31]
	ds_read_b64_tr_b16 v[180:181], v205 offset:35008
	ds_read_b64_tr_b16 v[182:183], v205 offset:37568
	s_waitcnt lgkmcnt(12)
	v_mfma_f32_32x32x16_bf16 v[16:31], v[184:187], v[88:91], v[16:31]
	ds_read_b64_tr_b16 v[184:185], v205 offset:40128
	ds_read_b64_tr_b16 v[186:187], v205 offset:42688
	s_waitcnt lgkmcnt(12)
	v_mfma_f32_32x32x16_bf16 v[16:31], v[96:99], v[92:95], v[16:31]
	ds_read_b64_tr_b16 v[96:97], v205 offset:45248
	ds_read_b64_tr_b16 v[98:99], v205 offset:47808
	s_waitcnt lgkmcnt(12)
	v_mfma_f32_32x32x16_bf16 v[0:15], v[100:103], v[80:83], v[0:15]
	ds_read_b64_tr_b16 v[100:101], v205 offset:50368
	ds_read_b64_tr_b16 v[102:103], v205 offset:52928
	s_waitcnt lgkmcnt(12)
	v_mfma_f32_32x32x16_bf16 v[0:15], v[104:107], v[84:87], v[0:15]
	ds_read_b128 v[210:213], v206 offset:8704
	ds_read_b128 v[104:107], v206 offset:8736
	s_waitcnt lgkmcnt(12)
	v_mfma_f32_32x32x16_bf16 v[0:15], v[108:111], v[88:91], v[0:15]
	ds_read_b128 v[108:111], v206 offset:8768
	ds_read_b128 v[188:191], v206
	s_waitcnt lgkmcnt(12)
	v_mfma_f32_32x32x16_bf16 v[0:15], v[176:179], v[92:95], v[0:15]
	ds_read_b128 v[176:179], v206 offset:8800
	ds_read_b128 v[224:227], v206 offset:32
	s_waitcnt lgkmcnt(12)
	v_mfma_f32_32x32x16_bf16 v[48:63], v[180:183], v[80:83], v[48:63]
	ds_read_b128 v[228:231], v206 offset:64
	ds_read_b128 v[248:251], v206 offset:96
	s_waitcnt lgkmcnt(12)
	v_mfma_f32_32x32x16_bf16 v[48:63], v[184:187], v[84:87], v[48:63]
	s_waitcnt lgkmcnt(10)
	v_mfma_f32_32x32x16_bf16 v[48:63], v[96:99], v[88:91], v[48:63]
	s_waitcnt lgkmcnt(8)
	v_mfma_f32_32x32x16_bf16 v[48:63], v[100:103], v[92:95], v[48:63]
	s_waitcnt lgkmcnt(7)
	v_mfma_f32_32x32x16_bf16 v[80:95], v[210:213], v[112:115], v[64:79]
	s_waitcnt lgkmcnt(6)
	v_mfma_f32_32x32x16_bf16 v[80:95], v[104:107], v[116:119], v[80:95]
	s_waitcnt lgkmcnt(5)
	v_mfma_f32_32x32x16_bf16 v[80:95], v[108:111], v[120:123], v[80:95]
	s_waitcnt lgkmcnt(3)
	v_mfma_f32_32x32x16_bf16 v[80:95], v[176:179], v[124:127], v[80:95]
	s_waitcnt lgkmcnt(4)
	v_mfma_f32_32x32x16_bf16 v[96:111], v[188:191], v[112:115], v[64:79]
	s_waitcnt lgkmcnt(2)
	v_mfma_f32_32x32x16_bf16 v[96:111], v[224:227], v[116:119], v[96:111]
	s_waitcnt lgkmcnt(1)
	v_mfma_f32_32x32x16_bf16 v[96:111], v[228:231], v[120:123], v[96:111]
	s_waitcnt lgkmcnt(0)
	v_mfma_f32_32x32x16_bf16 v[96:111], v[248:251], v[124:127], v[96:111]
	s_setprio 0
	s_cmp_gt_i32 s33, 3
	s_cbranch_scc0 .Lbn_b1
.LB1_end:
	s_addk_i32 s68, 0x100
	s_add_i32 s65, s65, 1
	s_add_i32 s33, s33, -1
	s_cmp_eq_u32 s21, s68
	s_cbranch_scc1 .LB1_exit
.LB2_top:
	s_cmp_ge_u32 s65, s66
	s_cbranch_scc1 .Lnod_b2
	s_add_i32 s4, s65, 1
	s_cmp_ge_u32 s4, s66
	s_cbranch_scc1 .Lvo_b2
	s_add_i32 m0, s32, 0x4400
	s_nop 0
	global_load_lds_dwordx4 v128, s[80:81]
	s_add_i32 m0, m0, 0x2000
	s_nop 0
	global_load_lds_dwordx4 v129, s[80:81]
	s_add_i32 m0, s32, 0x8800
	s_nop 0
	global_load_lds_dwordx4 v130, s[80:81]
	s_add_i32 m0, m0, 0x2000
	s_nop 0
	global_load_lds_dwordx4 v131, s[80:81]
	s_cmp_eq_u32 s56, 0
	s_cbranch_scc1 .LkX_b2
	s_add_i32 m0, s32, 0xc400
	s_nop 0
	global_load_lds_dwordx4 v132, s[80:81]

.Latt_b2_exp:
	v_exp_f32_e32 v96, v96
	v_exp_f32_e32 v97, v97
	v_exp_f32_e32 v176, v80
	v_exp_f32_e32 v177, v81
	v_exp_f32_e32 v98, v98
	v_exp_f32_e32 v99, v99
	v_exp_f32_e32 v178, v82
	v_exp_f32_e32 v179, v83
	v_exp_f32_e32 v100, v100
	v_exp_f32_e32 v101, v101
	v_exp_f32_e32 v180, v84
	v_exp_f32_e32 v181, v85
	v_exp_f32_e32 v102, v102
	v_exp_f32_e32 v103, v103
	v_exp_f32_e32 v182, v86
	v_exp_f32_e32 v183, v87
	v_exp_f32_e32 v104, v104
	v_exp_f32_e32 v105, v105
	v_exp_f32_e32 v184, v88
	v_exp_f32_e32 v185, v89
	v_exp_f32_e32 v106, v106
	v_exp_f32_e32 v107, v107
	v_exp_f32_e32 v186, v90
	v_exp_f32_e32 v187, v91
	v_exp_f32_e32 v108, v108
	v_exp_f32_e32 v109, v109
	v_exp_f32_e32 v188, v92
	v_exp_f32_e32 v189, v93
	v_exp_f32_e32 v110, v110
	v_exp_f32_e32 v111, v111
	v_exp_f32_e32 v190, v94
	v_exp_f32_e32 v191, v95
	v_cvt_pk_bf16_f32 v80, v96, v97
	v_cvt_pk_bf16_f32 v81, v98, v99
	v_cvt_pk_bf16_f32 v82, v100, v101
	v_cvt_pk_bf16_f32 v83, v102, v103
	v_cvt_pk_bf16_f32 v84, v104, v105
	v_cvt_pk_bf16_f32 v85, v106, v107
	v_cvt_pk_bf16_f32 v86, v108, v109
	v_cvt_pk_bf16_f32 v87, v110, v111
	v_cvt_pk_bf16_f32 v88, v176, v177
	v_cvt_pk_bf16_f32 v89, v178, v179
	v_cvt_pk_bf16_f32 v90, v180, v181
	v_cvt_pk_bf16_f32 v91, v182, v183
	v_cvt_pk_bf16_f32 v92, v184, v185
	v_cvt_pk_bf16_f32 v93, v186, v187
	v_cvt_pk_bf16_f32 v94, v188, v189
	v_cvt_pk_bf16_f32 v95, v190, v191
	v_pk_add_f32 v[96:97], v[96:97], v[100:101]
	v_pk_add_f32 v[98:99], v[98:99], v[102:103]
	v_pk_add_f32 v[176:177], v[176:177], v[180:181]
	v_pk_add_f32 v[178:179], v[178:179], v[182:183]
	v_pk_add_f32 v[96:97], v[96:97], v[104:105]
	v_pk_add_f32 v[98:99], v[98:99], v[106:107]
	v_pk_add_f32 v[176:177], v[176:177], v[184:185]
	v_pk_add_f32 v[178:179], v[178:179], v[186:187]
	v_pk_add_f32 v[96:97], v[96:97], v[108:109]
	v_pk_add_f32 v[98:99], v[98:99], v[110:111]
	v_pk_add_f32 v[176:177], v[176:177], v[188:189]
	v_pk_add_f32 v[178:179], v[178:179], v[190:191]
	v_pk_add_f32 v[96:97], v[96:97], v[98:99]
	v_pk_add_f32 v[176:177], v[176:177], v[178:179]
	s_nop 0
	v_pk_add_f32 v[96:97], v[96:97], v[176:177]
	s_nop 0
	v_add_f32_e32 v96, v96, v97
	v_add_f32_e32 v172, v172, v96
	s_cmp_ge_i32 s65, s86
	s_cbranch_scc1 .LB2_pvonly
	v_add_u32_e32 v205, 0xa000, v165
	v_add_u32_e32 v206, 0x0, v192
	s_add_i32 s4, s65, 1
	s_cmp_lt_u32 s4, s66
	s_cbranch_scc0 .Lw0_b2
	s_waitcnt vmcnt(5) lgkmcnt(0)

.LB0_top:
	s_cmp_ge_u32 s65, s66
	s_cbranch_scc1 .Lnod_b0
	s_add_i32 s4, s65, 1
	s_cmp_ge_u32 s4, s66
	s_cbranch_scc1 .Lvo_b0
	s_add_i32 m0, s32, 0x20400
	s_nop 0
	global_load_lds_dwordx4 v128, s[80:81]
	s_add_i32 m0, m0, 0x2000
	s_nop 0
	global_load_lds_dwordx4 v129, s[80:81]
	s_add_i32 m0, s32, 0xd800
	s_nop 0
	global_load_lds_dwordx4 v130, s[80:81]
	s_add_i32 m0, m0, 0x2000
	s_nop 0
	global_load_lds_dwordx4 v131, s[80:81]
	s_cmp_eq_u32 s56, 0
	s_cbranch_scc1 .LkX_b0
	s_add_i32 m0, s32, 0x11400
	s_nop 0
	global_load_lds_dwordx4 v132, s[80:81]

.Latt_b0_exp:
	v_exp_f32_e32 v96, v96
	v_exp_f32_e32 v97, v97
	v_exp_f32_e32 v176, v80
	v_exp_f32_e32 v177, v81
	v_exp_f32_e32 v98, v98
	v_exp_f32_e32 v99, v99
	v_exp_f32_e32 v178, v82
	v_exp_f32_e32 v179, v83
	v_exp_f32_e32 v100, v100
	v_exp_f32_e32 v101, v101
	v_exp_f32_e32 v180, v84
	v_exp_f32_e32 v181, v85
	v_exp_f32_e32 v102, v102
	v_exp_f32_e32 v103, v103
	v_exp_f32_e32 v182, v86
	v_exp_f32_e32 v183, v87
	v_exp_f32_e32 v104, v104
	v_exp_f32_e32 v105, v105
	v_exp_f32_e32 v184, v88
	v_exp_f32_e32 v185, v89
	v_exp_f32_e32 v106, v106
	v_exp_f32_e32 v107, v107
	v_exp_f32_e32 v186, v90
	v_exp_f32_e32 v187, v91
	v_exp_f32_e32 v108, v108
	v_exp_f32_e32 v109, v109
	v_exp_f32_e32 v188, v92
	v_exp_f32_e32 v189, v93
	v_exp_f32_e32 v110, v110
	v_exp_f32_e32 v111, v111
	v_exp_f32_e32 v190, v94
	v_exp_f32_e32 v191, v95
	v_cvt_pk_bf16_f32 v80, v96, v97
	v_cvt_pk_bf16_f32 v81, v98, v99
	v_cvt_pk_bf16_f32 v82, v100, v101
	v_cvt_pk_bf16_f32 v83, v102, v103
	v_cvt_pk_bf16_f32 v84, v104, v105
	v_cvt_pk_bf16_f32 v85, v106, v107
	v_cvt_pk_bf16_f32 v86, v108, v109
	v_cvt_pk_bf16_f32 v87, v110, v111
	v_cvt_pk_bf16_f32 v88, v176, v177
	v_cvt_pk_bf16_f32 v89, v178, v179
	v_cvt_pk_bf16_f32 v90, v180, v181
	v_cvt_pk_bf16_f32 v91, v182, v183
	v_cvt_pk_bf16_f32 v92, v184, v185
	v_cvt_pk_bf16_f32 v93, v186, v187
	v_cvt_pk_bf16_f32 v94, v188, v189
	v_cvt_pk_bf16_f32 v95, v190, v191
	v_pk_add_f32 v[96:97], v[96:97], v[100:101]
	v_pk_add_f32 v[98:99], v[98:99], v[102:103]
	v_pk_add_f32 v[176:177], v[176:177], v[180:181]
	v_pk_add_f32 v[178:179], v[178:179], v[182:183]
	v_pk_add_f32 v[96:97], v[96:97], v[104:105]
	v_pk_add_f32 v[98:99], v[98:99], v[106:107]
	v_pk_add_f32 v[176:177], v[176:177], v[184:185]
	v_pk_add_f32 v[178:179], v[178:179], v[186:187]
	v_pk_add_f32 v[96:97], v[96:97], v[108:109]
	v_pk_add_f32 v[98:99], v[98:99], v[110:111]
	v_pk_add_f32 v[176:177], v[176:177], v[188:189]
	v_pk_add_f32 v[178:179], v[178:179], v[190:191]
	v_pk_add_f32 v[96:97], v[96:97], v[98:99]
	v_pk_add_f32 v[176:177], v[176:177], v[178:179]
	s_nop 0
	v_pk_add_f32 v[96:97], v[96:97], v[176:177]
	s_nop 0
	v_add_f32_e32 v96, v96, v97
	v_add_f32_e32 v172, v172, v96
	s_cmp_ge_i32 s65, s86
	s_cbranch_scc1 .LB0_pvonly
	v_add_u32_e32 v205, 0x0, v165
	v_add_u32_e32 v206, 0x4400, v192
	s_add_i32 s4, s65, 1
	s_cmp_lt_u32 s4, s66
	s_cbranch_scc0 .Lw0_b0
	s_waitcnt vmcnt(5) lgkmcnt(0)

.LB0_end:
	s_addk_i32 s68, 0x100
	s_add_i32 s65, s65, 1
	s_add_i32 s33, s33, -1
	s_cmp_eq_u32 s21, s68
	s_cbranch_scc1 .LB0_exit
	s_branch .LB1_top
.LA1_top:
	v_add_u32_e32 v205, 0x0, v165
	v_add_u32_e32 v206, 0x4400, v192
	ds_read_b64_tr_b16 v[96:97], v205 offset:34816
	ds_read_b64_tr_b16 v[98:99], v205 offset:37376
	ds_read_b64_tr_b16 v[100:101], v205 offset:39936
	ds_read_b64_tr_b16 v[102:103], v205 offset:42496
	ds_read_b64_tr_b16 v[104:105], v205 offset:45056
	ds_read_b64_tr_b16 v[106:107], v205 offset:47616
	ds_read_b64_tr_b16 v[108:109], v205 offset:50176
	ds_read_b64_tr_b16 v[110:111], v205 offset:52736
	ds_read_b64_tr_b16 v[176:177], v205 offset:34880
	ds_read_b64_tr_b16 v[178:179], v205 offset:37440
	ds_read_b64_tr_b16 v[180:181], v205 offset:40000
	ds_read_b64_tr_b16 v[182:183], v205 offset:42560
	ds_read_b64_tr_b16 v[184:185], v205 offset:45120
	ds_read_b64_tr_b16 v[186:187], v205 offset:47680
	s_setprio 1
	s_waitcnt lgkmcnt(12)
	v_mfma_f32_32x32x16_bf16 v[32:47], v[96:99], v[80:83], v[32:47]
	ds_read_b64_tr_b16 v[96:97], v205 offset:50240
	ds_read_b64_tr_b16 v[98:99], v205 offset:52800
	s_waitcnt lgkmcnt(12)
	v_mfma_f32_32x32x16_bf16 v[32:47], v[100:103], v[84:87], v[32:47]
	ds_read_b64_tr_b16 v[100:101], v205 offset:34944
	ds_read_b64_tr_b16 v[102:103], v205 offset:37504
	s_waitcnt lgkmcnt(12)
	v_mfma_f32_32x32x16_bf16 v[32:47], v[104:107], v[88:91], v[32:47]
	ds_read_b64_tr_b16 v[104:105], v205 offset:40064
	ds_read_b64_tr_b16 v[106:107], v205 offset:42624
	s_waitcnt lgkmcnt(12)
	v_mfma_f32_32x32x16_bf16 v[32:47], v[108:111], v[92:95], v[32:47]
	ds_read_b64_tr_b16 v[108:109], v205 offset:45184
	ds_read_b64_tr_b16 v[110:111], v205 offset:47744
	s_waitcnt lgkmcnt(12)
	v_mfma_f32_32x32x16_bf16 v[16:31], v[176:179], v[80:83], v[16:31]
	ds_read_b64_tr_b16 v[176:177], v205 offset:50304
	ds_read_b64_tr_b16 v[178:179], v205 offset:52864
	s_waitcnt lgkmcnt(12)
	v_mfma_f32_32x32x16_bf16 v[16:31], v[180:183], v[84:87], v[16:31]
	ds_read_b64_tr_b16 v[180:181], v205 offset:35008
	ds_read_b64_tr_b16 v[182:183], v205 offset:37568
	s_waitcnt lgkmcnt(12)
	v_mfma_f32_32x32x16_bf16 v[16:31], v[184:187], v[88:91], v[16:31]
	ds_read_b64_tr_b16 v[184:185], v205 offset:40128
	ds_read_b64_tr_b16 v[186:187], v205 offset:42688
	s_waitcnt lgkmcnt(12)
	v_mfma_f32_32x32x16_bf16 v[16:31], v[96:99], v[92:95], v[16:31]
	ds_read_b64_tr_b16 v[96:97], v205 offset:45248
	ds_read_b64_tr_b16 v[98:99], v205 offset:47808
	s_waitcnt lgkmcnt(12)
	v_mfma_f32_32x32x16_bf16 v[0:15], v[100:103], v[80:83], v[0:15]
	ds_read_b64_tr_b16 v[100:101], v205 offset:50368
	ds_read_b64_tr_b16 v[102:103], v205 offset:52928
	s_waitcnt lgkmcnt(12)
	v_mfma_f32_32x32x16_bf16 v[0:15], v[104:107], v[84:87], v[0:15]
	ds_read_b128 v[210:213], v206 offset:8704
	ds_read_b128 v[104:107], v206 offset:8736
	s_waitcnt lgkmcnt(12)
	v_mfma_f32_32x32x16_bf16 v[0:15], v[108:111], v[88:91], v[0:15]
	ds_read_b128 v[108:111], v206 offset:8768
	ds_read_b128 v[188:191], v206
	s_waitcnt lgkmcnt(12)
	v_mfma_f32_32x32x16_bf16 v[0:15], v[176:179], v[92:95], v[0:15]
	ds_read_b128 v[176:179], v206 offset:8800
	ds_read_b128 v[224:227], v206 offset:32
	s_waitcnt lgkmcnt(12)
	v_mfma_f32_32x32x16_bf16 v[48:63], v[180:183], v[80:83], v[48:63]
	ds_read_b128 v[228:231], v206 offset:64
	ds_read_b128 v[248:251], v206 offset:96
	s_waitcnt lgkmcnt(12)
	v_mfma_f32_32x32x16_bf16 v[48:63], v[184:187], v[84:87], v[48:63]
	s_waitcnt lgkmcnt(10)
	v_mfma_f32_32x32x16_bf16 v[48:63], v[96:99], v[88:91], v[48:63]
	s_waitcnt lgkmcnt(8)
	v_mfma_f32_32x32x16_bf16 v[48:63], v[100:103], v[92:95], v[48:63]
	s_waitcnt lgkmcnt(7)
	v_mfma_f32_32x32x16_bf16 v[80:95], v[210:213], v[112:115], v[64:79]
	s_waitcnt lgkmcnt(6)
	v_mfma_f32_32x32x16_bf16 v[80:95], v[104:107], v[116:119], v[80:95]
	s_waitcnt lgkmcnt(5)
	v_mfma_f32_32x32x16_bf16 v[80:95], v[108:111], v[120:123], v[80:95]
	s_waitcnt lgkmcnt(3)
	v_mfma_f32_32x32x16_bf16 v[80:95], v[176:179], v[124:127], v[80:95]
	s_waitcnt lgkmcnt(4)
	v_mfma_f32_32x32x16_bf16 v[96:111], v[188:191], v[112:115], v[64:79]
	s_waitcnt lgkmcnt(2)
	v_mfma_f32_32x32x16_bf16 v[96:111], v[224:227], v[116:119], v[96:111]
	s_waitcnt lgkmcnt(1)
	v_mfma_f32_32x32x16_bf16 v[96:111], v[228:231], v[120:123], v[96:111]
	s_waitcnt lgkmcnt(0)
	v_mfma_f32_32x32x16_bf16 v[96:111], v[248:251], v[124:127], v[96:111]
	s_setprio 0
	s_cmp_gt_i32 s33, 2
	s_cbranch_scc0 .Lba_a1
.Latt_a1_stg:
	s_add_i32 s4, s65, 1
	s_cmp_lt_u32 s4, s66
	s_cbranch_scc0 .Lw0_a1
	s_cmp_eq_u32 s56, 4
	s_cbranch_scc1 .Lw5_a1
	s_waitcnt vmcnt(4) lgkmcnt(0)
.Lwd_a1:
	s_barrier
	s_add_i32 s4, s65, 1
	s_cmp_ge_u32 s4, s66
	s_cbranch_scc1 .Lnodx_a1
	s_add_i32 s4, s65, 2
	s_cmp_ge_u32 s4, s66
	s_cbranch_scc1 .Lvo_a1
	s_add_i32 m0, s32, 0x4400
	s_nop 0
	global_load_lds_dwordx4 v128, s[80:81]
	s_add_i32 m0, m0, 0x2000
	s_nop 0
	global_load_lds_dwordx4 v129, s[80:81]
	s_add_i32 m0, s32, 0x8800
	s_nop 0
	global_load_lds_dwordx4 v130, s[80:81]
	s_add_i32 m0, m0, 0x2000
	s_nop 0
	global_load_lds_dwordx4 v131, s[80:81]
	s_cmp_eq_u32 s56, 4
	s_cbranch_scc1 .LvX_a1

.Lnod_a1:
	v_max_f32_e32 v176, v96, v80
	v_max3_f32 v177, v81, v98, v82
	v_max3_f32 v176, v176, v97, v99
	v_max3_f32 v177, v177, v100, v84
	v_max3_f32 v176, v176, v83, v101
	v_max3_f32 v177, v177, v102, v86
	v_max3_f32 v176, v176, v85, v103
	v_max3_f32 v177, v177, v104, v88
	v_max3_f32 v176, v176, v87, v105
	v_max3_f32 v177, v177, v106, v90
	v_max3_f32 v176, v176, v89, v107
	v_max3_f32 v177, v177, v108, v92
	v_max3_f32 v176, v176, v91, v109
	v_max3_f32 v177, v177, v110, v94
	v_max3_f32 v176, v176, v93, v111
	v_max3_f32 v176, v176, v95, v177
	v_mov_b32_e32 v177, v176
	s_nop 1
	v_permlane32_swap_b32_e32 v176, v177
	v_max_f32_e32 v176, v176, v177
	v_cmp_lt_f32_e32 vcc, 0x41000000, v176
	s_cbranch_vccnz .Lrs_a1

.LA2_top:
	v_add_u32_e32 v205, 0x5000, v165
	v_add_u32_e32 v206, 0x20400, v192
	ds_read_b64_tr_b16 v[96:97], v205 offset:34816
	ds_read_b64_tr_b16 v[98:99], v205 offset:37376
	ds_read_b64_tr_b16 v[100:101], v205 offset:39936
	ds_read_b64_tr_b16 v[102:103], v205 offset:42496
	ds_read_b64_tr_b16 v[104:105], v205 offset:45056
	ds_read_b64_tr_b16 v[106:107], v205 offset:47616
	ds_read_b64_tr_b16 v[108:109], v205 offset:50176
	ds_read_b64_tr_b16 v[110:111], v205 offset:52736
	ds_read_b64_tr_b16 v[176:177], v205 offset:34880
	ds_read_b64_tr_b16 v[178:179], v205 offset:37440
	ds_read_b64_tr_b16 v[180:181], v205 offset:40000
	ds_read_b64_tr_b16 v[182:183], v205 offset:42560
	ds_read_b64_tr_b16 v[184:185], v205 offset:45120
	ds_read_b64_tr_b16 v[186:187], v205 offset:47680
	s_setprio 1
	s_waitcnt lgkmcnt(12)
	v_mfma_f32_32x32x16_bf16 v[32:47], v[96:99], v[80:83], v[32:47]
	ds_read_b64_tr_b16 v[96:97], v205 offset:50240
	ds_read_b64_tr_b16 v[98:99], v205 offset:52800
	s_waitcnt lgkmcnt(12)
	v_mfma_f32_32x32x16_bf16 v[32:47], v[100:103], v[84:87], v[32:47]
	ds_read_b64_tr_b16 v[100:101], v205 offset:34944
	ds_read_b64_tr_b16 v[102:103], v205 offset:37504
	s_waitcnt lgkmcnt(12)
	v_mfma_f32_32x32x16_bf16 v[32:47], v[104:107], v[88:91], v[32:47]
	ds_read_b64_tr_b16 v[104:105], v205 offset:40064
	ds_read_b64_tr_b16 v[106:107], v205 offset:42624
	s_waitcnt lgkmcnt(12)
	v_mfma_f32_32x32x16_bf16 v[32:47], v[108:111], v[92:95], v[32:47]
	ds_read_b64_tr_b16 v[108:109], v205 offset:45184
	ds_read_b64_tr_b16 v[110:111], v205 offset:47744
	s_waitcnt lgkmcnt(12)
	v_mfma_f32_32x32x16_bf16 v[16:31], v[176:179], v[80:83], v[16:31]
	ds_read_b64_tr_b16 v[176:177], v205 offset:50304
	ds_read_b64_tr_b16 v[178:179], v205 offset:52864
	s_waitcnt lgkmcnt(12)
	v_mfma_f32_32x32x16_bf16 v[16:31], v[180:183], v[84:87], v[16:31]
	ds_read_b64_tr_b16 v[180:181], v205 offset:35008
	ds_read_b64_tr_b16 v[182:183], v205 offset:37568
	s_waitcnt lgkmcnt(12)
	v_mfma_f32_32x32x16_bf16 v[16:31], v[184:187], v[88:91], v[16:31]
	ds_read_b64_tr_b16 v[184:185], v205 offset:40128
	ds_read_b64_tr_b16 v[186:187], v205 offset:42688
	s_waitcnt lgkmcnt(12)
	v_mfma_f32_32x32x16_bf16 v[16:31], v[96:99], v[92:95], v[16:31]
	ds_read_b64_tr_b16 v[96:97], v205 offset:45248
	ds_read_b64_tr_b16 v[98:99], v205 offset:47808
	s_waitcnt lgkmcnt(12)
	v_mfma_f32_32x32x16_bf16 v[0:15], v[100:103], v[80:83], v[0:15]
	ds_read_b64_tr_b16 v[100:101], v205 offset:50368
	ds_read_b64_tr_b16 v[102:103], v205 offset:52928
	s_waitcnt lgkmcnt(12)
	v_mfma_f32_32x32x16_bf16 v[0:15], v[104:107], v[84:87], v[0:15]
	ds_read_b128 v[210:213], v206 offset:8704
	ds_read_b128 v[104:107], v206 offset:8736
	s_waitcnt lgkmcnt(12)
	v_mfma_f32_32x32x16_bf16 v[0:15], v[108:111], v[88:91], v[0:15]
	ds_read_b128 v[108:111], v206 offset:8768
	ds_read_b128 v[188:191], v206
	s_waitcnt lgkmcnt(12)
	v_mfma_f32_32x32x16_bf16 v[0:15], v[176:179], v[92:95], v[0:15]
	ds_read_b128 v[176:179], v206 offset:8800
	ds_read_b128 v[224:227], v206 offset:32
	s_waitcnt lgkmcnt(12)
	v_mfma_f32_32x32x16_bf16 v[48:63], v[180:183], v[80:83], v[48:63]
	ds_read_b128 v[228:231], v206 offset:64
	ds_read_b128 v[248:251], v206 offset:96
	s_waitcnt lgkmcnt(12)
	v_mfma_f32_32x32x16_bf16 v[48:63], v[184:187], v[84:87], v[48:63]
	s_waitcnt lgkmcnt(10)
	v_mfma_f32_32x32x16_bf16 v[48:63], v[96:99], v[88:91], v[48:63]
	s_waitcnt lgkmcnt(8)
	v_mfma_f32_32x32x16_bf16 v[48:63], v[100:103], v[92:95], v[48:63]
	s_waitcnt lgkmcnt(7)
	v_mfma_f32_32x32x16_bf16 v[80:95], v[210:213], v[112:115], v[64:79]
	s_waitcnt lgkmcnt(6)
	v_mfma_f32_32x32x16_bf16 v[80:95], v[104:107], v[116:119], v[80:95]
	s_waitcnt lgkmcnt(5)
	v_mfma_f32_32x32x16_bf16 v[80:95], v[108:111], v[120:123], v[80:95]
	s_waitcnt lgkmcnt(3)
	v_mfma_f32_32x32x16_bf16 v[80:95], v[176:179], v[124:127], v[80:95]
	s_waitcnt lgkmcnt(4)
	v_mfma_f32_32x32x16_bf16 v[96:111], v[188:191], v[112:115], v[64:79]
	s_waitcnt lgkmcnt(2)
	v_mfma_f32_32x32x16_bf16 v[96:111], v[224:227], v[116:119], v[96:111]
	s_waitcnt lgkmcnt(1)
	v_mfma_f32_32x32x16_bf16 v[96:111], v[228:231], v[120:123], v[96:111]
	s_waitcnt lgkmcnt(0)
	v_mfma_f32_32x32x16_bf16 v[96:111], v[248:251], v[124:127], v[96:111]
	s_setprio 0
	s_cmp_gt_i32 s33, 2
	s_cbranch_scc0 .Lba_a2

.Lwd_a2:
	s_barrier
	s_add_i32 s4, s65, 1
	s_cmp_ge_u32 s4, s66
	s_cbranch_scc1 .Lnodx_a2
	s_add_i32 s4, s65, 2
	s_cmp_ge_u32 s4, s66
	s_cbranch_scc1 .Lvo_a2
	s_add_i32 m0, s32, 0x20400
	s_nop 0
	global_load_lds_dwordx4 v128, s[80:81]
	s_add_i32 m0, m0, 0x2000
	s_nop 0
	global_load_lds_dwordx4 v129, s[80:81]
	s_add_i32 m0, s32, 0xd800
	s_nop 0
	global_load_lds_dwordx4 v130, s[80:81]
	s_add_i32 m0, m0, 0x2000
	s_nop 0
	global_load_lds_dwordx4 v131, s[80:81]
	s_cmp_eq_u32 s56, 4
	s_cbranch_scc1 .LvX_a2

.LA0_top:
	v_add_u32_e32 v205, 0xa000, v165
	v_add_u32_e32 v206, 0x0, v192
	ds_read_b64_tr_b16 v[96:97], v205 offset:34816
	ds_read_b64_tr_b16 v[98:99], v205 offset:37376
	ds_read_b64_tr_b16 v[100:101], v205 offset:39936
	ds_read_b64_tr_b16 v[102:103], v205 offset:42496
	ds_read_b64_tr_b16 v[104:105], v205 offset:45056
	ds_read_b64_tr_b16 v[106:107], v205 offset:47616
	ds_read_b64_tr_b16 v[108:109], v205 offset:50176
	ds_read_b64_tr_b16 v[110:111], v205 offset:52736
	ds_read_b64_tr_b16 v[176:177], v205 offset:34880
	ds_read_b64_tr_b16 v[178:179], v205 offset:37440
	ds_read_b64_tr_b16 v[180:181], v205 offset:40000
	ds_read_b64_tr_b16 v[182:183], v205 offset:42560
	ds_read_b64_tr_b16 v[184:185], v205 offset:45120
	ds_read_b64_tr_b16 v[186:187], v205 offset:47680
	s_setprio 1
	s_waitcnt lgkmcnt(12)
	v_mfma_f32_32x32x16_bf16 v[32:47], v[96:99], v[80:83], v[32:47]
	ds_read_b64_tr_b16 v[96:97], v205 offset:50240
	ds_read_b64_tr_b16 v[98:99], v205 offset:52800
	s_waitcnt lgkmcnt(12)
	v_mfma_f32_32x32x16_bf16 v[32:47], v[100:103], v[84:87], v[32:47]
	ds_read_b64_tr_b16 v[100:101], v205 offset:34944
	ds_read_b64_tr_b16 v[102:103], v205 offset:37504
	s_waitcnt lgkmcnt(12)
	v_mfma_f32_32x32x16_bf16 v[32:47], v[104:107], v[88:91], v[32:47]
	ds_read_b64_tr_b16 v[104:105], v205 offset:40064
	ds_read_b64_tr_b16 v[106:107], v205 offset:42624
	s_waitcnt lgkmcnt(12)
	v_mfma_f32_32x32x16_bf16 v[32:47], v[108:111], v[92:95], v[32:47]
	ds_read_b64_tr_b16 v[108:109], v205 offset:45184
	ds_read_b64_tr_b16 v[110:111], v205 offset:47744
	s_waitcnt lgkmcnt(12)
	v_mfma_f32_32x32x16_bf16 v[16:31], v[176:179], v[80:83], v[16:31]
	ds_read_b64_tr_b16 v[176:177], v205 offset:50304
	ds_read_b64_tr_b16 v[178:179], v205 offset:52864
	s_waitcnt lgkmcnt(12)
	v_mfma_f32_32x32x16_bf16 v[16:31], v[180:183], v[84:87], v[16:31]
	ds_read_b64_tr_b16 v[180:181], v205 offset:35008
	ds_read_b64_tr_b16 v[182:183], v205 offset:37568
	s_waitcnt lgkmcnt(12)
	v_mfma_f32_32x32x16_bf16 v[16:31], v[184:187], v[88:91], v[16:31]
	ds_read_b64_tr_b16 v[184:185], v205 offset:40128
	ds_read_b64_tr_b16 v[186:187], v205 offset:42688
	s_waitcnt lgkmcnt(12)
	v_mfma_f32_32x32x16_bf16 v[16:31], v[96:99], v[92:95], v[16:31]
	ds_read_b64_tr_b16 v[96:97], v205 offset:45248
	ds_read_b64_tr_b16 v[98:99], v205 offset:47808
	s_waitcnt lgkmcnt(12)
	v_mfma_f32_32x32x16_bf16 v[0:15], v[100:103], v[80:83], v[0:15]
	ds_read_b64_tr_b16 v[100:101], v205 offset:50368
	ds_read_b64_tr_b16 v[102:103], v205 offset:52928
	s_waitcnt lgkmcnt(12)
	v_mfma_f32_32x32x16_bf16 v[0:15], v[104:107], v[84:87], v[0:15]
	ds_read_b128 v[210:213], v206 offset:8704
	ds_read_b128 v[104:107], v206 offset:8736
	s_waitcnt lgkmcnt(12)
	v_mfma_f32_32x32x16_bf16 v[0:15], v[108:111], v[88:91], v[0:15]
	ds_read_b128 v[108:111], v206 offset:8768
	ds_read_b128 v[188:191], v206
	s_waitcnt lgkmcnt(12)
	v_mfma_f32_32x32x16_bf16 v[0:15], v[176:179], v[92:95], v[0:15]
	ds_read_b128 v[176:179], v206 offset:8800
	ds_read_b128 v[224:227], v206 offset:32
	s_waitcnt lgkmcnt(12)
	v_mfma_f32_32x32x16_bf16 v[48:63], v[180:183], v[80:83], v[48:63]
	ds_read_b128 v[228:231], v206 offset:64
	ds_read_b128 v[248:251], v206 offset:96
	s_waitcnt lgkmcnt(12)
	v_mfma_f32_32x32x16_bf16 v[48:63], v[184:187], v[84:87], v[48:63]
	s_waitcnt lgkmcnt(10)
	v_mfma_f32_32x32x16_bf16 v[48:63], v[96:99], v[88:91], v[48:63]
	s_waitcnt lgkmcnt(8)
	v_mfma_f32_32x32x16_bf16 v[48:63], v[100:103], v[92:95], v[48:63]
	s_waitcnt lgkmcnt(7)
	v_mfma_f32_32x32x16_bf16 v[80:95], v[210:213], v[112:115], v[64:79]
	s_waitcnt lgkmcnt(6)
	v_mfma_f32_32x32x16_bf16 v[80:95], v[104:107], v[116:119], v[80:95]
	s_waitcnt lgkmcnt(5)
	v_mfma_f32_32x32x16_bf16 v[80:95], v[108:111], v[120:123], v[80:95]
	s_waitcnt lgkmcnt(3)
	v_mfma_f32_32x32x16_bf16 v[80:95], v[176:179], v[124:127], v[80:95]
	s_waitcnt lgkmcnt(4)
	v_mfma_f32_32x32x16_bf16 v[96:111], v[188:191], v[112:115], v[64:79]
	s_waitcnt lgkmcnt(2)
	v_mfma_f32_32x32x16_bf16 v[96:111], v[224:227], v[116:119], v[96:111]
	s_waitcnt lgkmcnt(1)
	v_mfma_f32_32x32x16_bf16 v[96:111], v[228:231], v[120:123], v[96:111]
	s_waitcnt lgkmcnt(0)
	v_mfma_f32_32x32x16_bf16 v[96:111], v[248:251], v[124:127], v[96:111]
	s_setprio 0
	s_cmp_gt_i32 s33, 2
	s_cbranch_scc0 .Lba_a0

.Lwd_a0:
	s_barrier
	s_add_i32 s4, s65, 1
	s_cmp_ge_u32 s4, s66
	s_cbranch_scc1 .Lnodx_a0
	s_add_i32 s4, s65, 2
	s_cmp_ge_u32 s4, s66
	s_cbranch_scc1 .Lvo_a0
	s_mov_b32 m0, s32
	s_nop 0
	global_load_lds_dwordx4 v128, s[80:81]
	s_add_i32 m0, m0, 0x2000
	s_nop 0
	global_load_lds_dwordx4 v129, s[80:81]
	s_add_i32 m0, s32, 0x12800
	s_nop 0
	global_load_lds_dwordx4 v130, s[80:81]
	s_add_i32 m0, m0, 0x2000
	s_nop 0
	global_load_lds_dwordx4 v131, s[80:81]
	s_cmp_eq_u32 s56, 4
	s_cbranch_scc1 .LvX_a0

.LkX_b1:
	s_mov_b32 m0, 0x4000
	s_nop 0
	global_load_lds_dwordx4 v132, s[80:81]
	s_branch .LXd_b1
.Lvo_b1:
	s_add_i32 m0, s32, 0x12800
	s_nop 0
	global_load_lds_dwordx4 v130, s[80:81]
	s_add_i32 m0, m0, 0x2000
	s_nop 0
	global_load_lds_dwordx4 v131, s[80:81]
	s_cmp_eq_u32 s56, 0
	s_cbranch_scc1 .Lvo2_b1
	s_add_i32 m0, s32, 0x16400
	s_nop 0
	global_load_lds_dwordx4 v132, s[80:81]

.Lw0_b1s:
	s_waitcnt vmcnt(0) lgkmcnt(0)
	s_branch .Lwd_b1s
.LB1_skip:
	s_add_i32 s4, s65, 1
	s_cmp_lt_u32 s4, s66
	s_cbranch_scc0 .Lw0_b1s
	s_waitcnt vmcnt(5) lgkmcnt(0)
.Lwd_b1s:
	s_barrier
	s_branch .LB1_end
.Lrs_b1:
	v_max_f32_e32 v64, v176, v176
	v_max_f32_e32 v66, 0, v64
	v_exp_f32_e64 v176, -v66
	v_add_f32_e32 v173, v173, v66
	v_xor_b32_e32 v64, 0x80000000, v173
	v_pk_add_f32 v[96:97], v[96:97], v[66:67] op_sel_hi:[1,0] neg_lo:[0,1] neg_hi:[0,1]
	v_pk_add_f32 v[80:81], v[80:81], v[66:67] op_sel_hi:[1,0] neg_lo:[0,1] neg_hi:[0,1]
	v_pk_add_f32 v[98:99], v[98:99], v[66:67] op_sel_hi:[1,0] neg_lo:[0,1] neg_hi:[0,1]
	v_pk_add_f32 v[82:83], v[82:83], v[66:67] op_sel_hi:[1,0] neg_lo:[0,1] neg_hi:[0,1]
	v_pk_add_f32 v[100:101], v[100:101], v[66:67] op_sel_hi:[1,0] neg_lo:[0,1] neg_hi:[0,1]
	v_pk_add_f32 v[84:85], v[84:85], v[66:67] op_sel_hi:[1,0] neg_lo:[0,1] neg_hi:[0,1]
	v_pk_add_f32 v[102:103], v[102:103], v[66:67] op_sel_hi:[1,0] neg_lo:[0,1] neg_hi:[0,1]
	v_pk_add_f32 v[86:87], v[86:87], v[66:67] op_sel_hi:[1,0] neg_lo:[0,1] neg_hi:[0,1]
	v_pk_add_f32 v[104:105], v[104:105], v[66:67] op_sel_hi:[1,0] neg_lo:[0,1] neg_hi:[0,1]
	v_pk_add_f32 v[88:89], v[88:89], v[66:67] op_sel_hi:[1,0] neg_lo:[0,1] neg_hi:[0,1]
	v_pk_add_f32 v[106:107], v[106:107], v[66:67] op_sel_hi:[1,0] neg_lo:[0,1] neg_hi:[0,1]
	v_pk_add_f32 v[90:91], v[90:91], v[66:67] op_sel_hi:[1,0] neg_lo:[0,1] neg_hi:[0,1]
	v_pk_add_f32 v[108:109], v[108:109], v[66:67] op_sel_hi:[1,0] neg_lo:[0,1] neg_hi:[0,1]
	v_pk_add_f32 v[92:93], v[92:93], v[66:67] op_sel_hi:[1,0] neg_lo:[0,1] neg_hi:[0,1]
	v_pk_add_f32 v[110:111], v[110:111], v[66:67] op_sel_hi:[1,0] neg_lo:[0,1] neg_hi:[0,1]
	v_pk_add_f32 v[94:95], v[94:95], v[66:67] op_sel_hi:[1,0] neg_lo:[0,1] neg_hi:[0,1]
	v_mov_b32_e32 v65, v64
	v_mov_b32_e32 v66, v64
	v_mov_b32_e32 v67, v64
	v_mov_b32_e32 v68, v64
	v_mov_b32_e32 v69, v64
	v_mov_b32_e32 v70, v64
	v_mov_b32_e32 v71, v64
	v_mov_b32_e32 v72, v64
	v_mov_b32_e32 v73, v64
	v_mov_b32_e32 v74, v64
	v_mov_b32_e32 v75, v64
	v_mov_b32_e32 v76, v64
	v_mov_b32_e32 v77, v64
	v_mov_b32_e32 v78, v64
	v_mov_b32_e32 v79, v64
	v_pk_mul_f32 v[46:47], v[46:47], v[176:177] op_sel_hi:[1,0]
	v_pk_mul_f32 v[44:45], v[44:45], v[176:177] op_sel_hi:[1,0]
	v_pk_mul_f32 v[42:43], v[42:43], v[176:177] op_sel_hi:[1,0]
	v_pk_mul_f32 v[40:41], v[40:41], v[176:177] op_sel_hi:[1,0]
	v_pk_mul_f32 v[38:39], v[38:39], v[176:177] op_sel_hi:[1,0]
	v_pk_mul_f32 v[36:37], v[36:37], v[176:177] op_sel_hi:[1,0]
	v_pk_mul_f32 v[34:35], v[34:35], v[176:177] op_sel_hi:[1,0]
	v_pk_mul_f32 v[32:33], v[32:33], v[176:177] op_sel_hi:[1,0]
	v_pk_mul_f32 v[30:31], v[30:31], v[176:177] op_sel_hi:[1,0]
	v_pk_mul_f32 v[28:29], v[28:29], v[176:177] op_sel_hi:[1,0]
	v_pk_mul_f32 v[26:27], v[26:27], v[176:177] op_sel_hi:[1,0]
	v_pk_mul_f32 v[24:25], v[24:25], v[176:177] op_sel_hi:[1,0]
	v_pk_mul_f32 v[22:23], v[22:23], v[176:177] op_sel_hi:[1,0]
	v_pk_mul_f32 v[20:21], v[20:21], v[176:177] op_sel_hi:[1,0]
	v_pk_mul_f32 v[18:19], v[18:19], v[176:177] op_sel_hi:[1,0]
	v_pk_mul_f32 v[16:17], v[16:17], v[176:177] op_sel_hi:[1,0]
	v_pk_mul_f32 v[14:15], v[14:15], v[176:177] op_sel_hi:[1,0]
	v_pk_mul_f32 v[12:13], v[12:13], v[176:177] op_sel_hi:[1,0]
	v_pk_mul_f32 v[10:11], v[10:11], v[176:177] op_sel_hi:[1,0]
	v_pk_mul_f32 v[8:9], v[8:9], v[176:177] op_sel_hi:[1,0]
	v_pk_mul_f32 v[6:7], v[6:7], v[176:177] op_sel_hi:[1,0]
	v_pk_mul_f32 v[4:5], v[4:5], v[176:177] op_sel_hi:[1,0]
	v_pk_mul_f32 v[2:3], v[2:3], v[176:177] op_sel_hi:[1,0]
	v_pk_mul_f32 v[0:1], v[0:1], v[176:177] op_sel_hi:[1,0]
	v_pk_mul_f32 v[62:63], v[62:63], v[176:177] op_sel_hi:[1,0]
	v_pk_mul_f32 v[60:61], v[60:61], v[176:177] op_sel_hi:[1,0]
	v_pk_mul_f32 v[58:59], v[58:59], v[176:177] op_sel_hi:[1,0]
	v_pk_mul_f32 v[56:57], v[56:57], v[176:177] op_sel_hi:[1,0]
	v_pk_mul_f32 v[54:55], v[54:55], v[176:177] op_sel_hi:[1,0]
	v_pk_mul_f32 v[52:53], v[52:53], v[176:177] op_sel_hi:[1,0]
	v_pk_mul_f32 v[50:51], v[50:51], v[176:177] op_sel_hi:[1,0]
	v_pk_mul_f32 v[48:49], v[48:49], v[176:177] op_sel_hi:[1,0]
	v_mul_f32_e32 v172, v172, v176
	s_branch .Latt_b1_exp

.Lwd_b1p:
	s_barrier
	s_mov_b32 s69, 1
	s_mul_i32 s4, s69, 0x5000
	v_add_u32_e32 v205, s4, v165
	ds_read_b64_tr_b16 v[224:225], v205 offset:34816
	ds_read_b64_tr_b16 v[226:227], v205 offset:37376
	ds_read_b64_tr_b16 v[228:229], v205 offset:39936
	ds_read_b64_tr_b16 v[230:231], v205 offset:42496
	ds_read_b64_tr_b16 v[248:249], v205 offset:45056
	ds_read_b64_tr_b16 v[250:251], v205 offset:47616
	ds_read_b64_tr_b16 v[210:211], v205 offset:50176
	ds_read_b64_tr_b16 v[212:213], v205 offset:52736
	s_setprio 1
	s_waitcnt lgkmcnt(6)
	v_mfma_f32_32x32x16_bf16 v[32:47], v[224:227], v[80:83], v[32:47]
	s_setprio 0
	ds_read_b64_tr_b16 v[224:225], v205 offset:34880
	ds_read_b64_tr_b16 v[226:227], v205 offset:37440
	s_setprio 1
	s_waitcnt lgkmcnt(6)
	v_mfma_f32_32x32x16_bf16 v[32:47], v[228:231], v[84:87], v[32:47]
	s_setprio 0
	ds_read_b64_tr_b16 v[228:229], v205 offset:40000
	ds_read_b64_tr_b16 v[230:231], v205 offset:42560
	s_setprio 1
	s_waitcnt lgkmcnt(6)
	v_mfma_f32_32x32x16_bf16 v[32:47], v[248:251], v[88:91], v[32:47]
	s_setprio 0
	ds_read_b64_tr_b16 v[248:249], v205 offset:45120
	ds_read_b64_tr_b16 v[250:251], v205 offset:47680
	s_setprio 1
	s_waitcnt lgkmcnt(6)
	v_mfma_f32_32x32x16_bf16 v[32:47], v[210:213], v[92:95], v[32:47]
	s_setprio 0
	ds_read_b64_tr_b16 v[210:211], v205 offset:50240
	ds_read_b64_tr_b16 v[212:213], v205 offset:52800
	s_setprio 1
	s_waitcnt lgkmcnt(6)
	v_mfma_f32_32x32x16_bf16 v[16:31], v[224:227], v[80:83], v[16:31]
	s_setprio 0
	ds_read_b64_tr_b16 v[224:225], v205 offset:34944
	ds_read_b64_tr_b16 v[226:227], v205 offset:37504
	s_setprio 1
	s_waitcnt lgkmcnt(6)
	v_mfma_f32_32x32x16_bf16 v[16:31], v[228:231], v[84:87], v[16:31]
	s_setprio 0
	ds_read_b64_tr_b16 v[228:229], v205 offset:40064
	ds_read_b64_tr_b16 v[230:231], v205 offset:42624
	s_setprio 1
	s_waitcnt lgkmcnt(6)
	v_mfma_f32_32x32x16_bf16 v[16:31], v[248:251], v[88:91], v[16:31]
	s_setprio 0
	ds_read_b64_tr_b16 v[248:249], v205 offset:45184
	ds_read_b64_tr_b16 v[250:251], v205 offset:47744
	s_setprio 1
	s_waitcnt lgkmcnt(6)
	v_mfma_f32_32x32x16_bf16 v[16:31], v[210:213], v[92:95], v[16:31]
	s_setprio 0
	ds_read_b64_tr_b16 v[210:211], v205 offset:50304
	ds_read_b64_tr_b16 v[212:213], v205 offset:52864
	s_setprio 1
	s_waitcnt lgkmcnt(6)
	v_mfma_f32_32x32x16_bf16 v[0:15], v[224:227], v[80:83], v[0:15]
	s_setprio 0
	ds_read_b64_tr_b16 v[224:225], v205 offset:35008
	ds_read_b64_tr_b16 v[226:227], v205 offset:37568
	s_setprio 1
	s_waitcnt lgkmcnt(6)
	v_mfma_f32_32x32x16_bf16 v[0:15], v[228:231], v[84:87], v[0:15]
	s_setprio 0
	ds_read_b64_tr_b16 v[228:229], v205 offset:40128
	ds_read_b64_tr_b16 v[230:231], v205 offset:42688
	s_setprio 1
	s_waitcnt lgkmcnt(6)
	v_mfma_f32_32x32x16_bf16 v[0:15], v[248:251], v[88:91], v[0:15]
	s_setprio 0
	ds_read_b64_tr_b16 v[248:249], v205 offset:45248
	ds_read_b64_tr_b16 v[250:251], v205 offset:47808
	s_setprio 1
	s_waitcnt lgkmcnt(6)
	v_mfma_f32_32x32x16_bf16 v[0:15], v[210:213], v[92:95], v[0:15]
	s_setprio 0
	ds_read_b64_tr_b16 v[210:211], v205 offset:50368
	ds_read_b64_tr_b16 v[212:213], v205 offset:52928
	s_setprio 1
	s_waitcnt lgkmcnt(6)
	v_mfma_f32_32x32x16_bf16 v[48:63], v[224:227], v[80:83], v[48:63]
	s_setprio 0
	s_setprio 1
	s_waitcnt lgkmcnt(4)
	v_mfma_f32_32x32x16_bf16 v[48:63], v[228:231], v[84:87], v[48:63]
	s_setprio 0
	s_setprio 1
	s_waitcnt lgkmcnt(2)
	v_mfma_f32_32x32x16_bf16 v[48:63], v[248:251], v[88:91], v[48:63]
	s_setprio 0
	s_setprio 1
	s_waitcnt lgkmcnt(0)
	v_mfma_f32_32x32x16_bf16 v[48:63], v[210:213], v[92:95], v[48:63]
	s_setprio 0
	s_branch .LB1_end

.Lbn_b1:
	s_waitcnt lgkmcnt(0)
	s_add_i32 s4, s68, 0x100
	v_add_u32_e32 v205, s4, v204
	v_add_u32_e32 v176, 0x17d00, v205
	v_add_u32_e32 v178, 0x17d80, v205
	ds_read2_b32 v[176:177], v176 offset1:1
	ds_read2_b32 v[178:179], v178 offset1:1
	v_add_u32_e32 v180, 0x17d08, v205
	v_add_u32_e32 v182, 0x17d88, v205
	v_add_u32_e32 v184, 0x17d20, v205
	v_add_u32_e32 v186, 0x17da0, v205
	v_add_u32_e32 v188, 0x17d28, v205
	v_add_u32_e32 v190, 0x17da8, v205
	v_add_u32_e32 v206, 0x17d40, v205
	v_add_u32_e32 v210, 0x17dc0, v205
	v_add_u32_e32 v212, 0x17d48, v205
	v_add_u32_e32 v221, 0x17dc8, v205
	ds_read2_b32 v[180:181], v180 offset1:1
	ds_read2_b32 v[182:183], v182 offset1:1
	ds_read2_b32 v[184:185], v184 offset1:1
	ds_read2_b32 v[186:187], v186 offset1:1
	ds_read2_b32 v[188:189], v188 offset1:1
	ds_read2_b32 v[190:191], v190 offset1:1
	ds_read2_b32 v[206:207], v206 offset1:1
	ds_read2_b32 v[210:211], v210 offset1:1
	ds_read2_b32 v[212:213], v212 offset1:1
	ds_read2_b32 v[224:225], v221 offset1:1
	v_add_u32_e32 v221, 0x17d60, v205
	v_add_u32_e32 v223, 0x17de0, v205
	ds_read2_b32 v[226:227], v221 offset1:1
	ds_read2_b32 v[228:229], v223 offset1:1
	v_add_u32_e32 v221, 0x17d68, v205
	v_add_u32_e32 v205, 0x17de8, v205
	ds_read2_b32 v[230:231], v221 offset1:1
	s_waitcnt lgkmcnt(14)
	v_pk_add_f32 v[96:97], v[96:97], v[176:177]
	ds_read2_b32 v[176:177], v205 offset1:1
	s_waitcnt lgkmcnt(3)
	v_pk_add_f32 v[108:109], v[108:109], v[226:227]
	v_pk_add_f32 v[106:107], v[106:107], v[212:213]
	s_waitcnt lgkmcnt(1)
	v_pk_add_f32 v[110:111], v[110:111], v[230:231]
	v_pk_add_f32 v[104:105], v[104:105], v[206:207]
	v_pk_add_f32 v[102:103], v[102:103], v[188:189]
	v_pk_add_f32 v[100:101], v[100:101], v[184:185]
	v_pk_add_f32 v[98:99], v[98:99], v[180:181]
	s_waitcnt lgkmcnt(0)
	v_pk_add_f32 v[94:95], v[94:95], v[176:177]
	v_pk_add_f32 v[92:93], v[92:93], v[228:229]
	v_pk_add_f32 v[90:91], v[90:91], v[224:225]
	v_pk_add_f32 v[88:89], v[88:89], v[210:211]
	v_pk_add_f32 v[86:87], v[86:87], v[190:191]
	v_pk_add_f32 v[84:85], v[84:85], v[186:187]
	v_pk_add_f32 v[82:83], v[82:83], v[182:183]
	v_pk_add_f32 v[80:81], v[80:81], v[178:179]
	s_nop 0
	s_branch .LB1_end

.LkX_b2:
	s_mov_b32 m0, 0x8400
	s_nop 0
	global_load_lds_dwordx4 v132, s[80:81]
	s_branch .LXd_b2
.Lvo_b2:
	s_add_i32 m0, s32, 0x8800
	s_nop 0
	global_load_lds_dwordx4 v130, s[80:81]
	s_add_i32 m0, m0, 0x2000
	s_nop 0
	global_load_lds_dwordx4 v131, s[80:81]
	s_cmp_eq_u32 s56, 0
	s_cbranch_scc1 .Lvo2_b2
	s_add_i32 m0, s32, 0xc400
	s_nop 0
	global_load_lds_dwordx4 v132, s[80:81]

.Lwd_b2p:
	s_barrier
	s_mov_b32 s69, 2
	s_mul_i32 s4, s69, 0x5000
	v_add_u32_e32 v205, s4, v165
	ds_read_b64_tr_b16 v[224:225], v205 offset:34816
	ds_read_b64_tr_b16 v[226:227], v205 offset:37376
	ds_read_b64_tr_b16 v[228:229], v205 offset:39936
	ds_read_b64_tr_b16 v[230:231], v205 offset:42496
	ds_read_b64_tr_b16 v[248:249], v205 offset:45056
	ds_read_b64_tr_b16 v[250:251], v205 offset:47616
	ds_read_b64_tr_b16 v[210:211], v205 offset:50176
	ds_read_b64_tr_b16 v[212:213], v205 offset:52736
	s_setprio 1
	s_waitcnt lgkmcnt(6)
	v_mfma_f32_32x32x16_bf16 v[32:47], v[224:227], v[80:83], v[32:47]
	s_setprio 0
	ds_read_b64_tr_b16 v[224:225], v205 offset:34880
	ds_read_b64_tr_b16 v[226:227], v205 offset:37440
	s_setprio 1
	s_waitcnt lgkmcnt(6)
	v_mfma_f32_32x32x16_bf16 v[32:47], v[228:231], v[84:87], v[32:47]
	s_setprio 0
	ds_read_b64_tr_b16 v[228:229], v205 offset:40000
	ds_read_b64_tr_b16 v[230:231], v205 offset:42560
	s_setprio 1
	s_waitcnt lgkmcnt(6)
	v_mfma_f32_32x32x16_bf16 v[32:47], v[248:251], v[88:91], v[32:47]
	s_setprio 0
	ds_read_b64_tr_b16 v[248:249], v205 offset:45120
	ds_read_b64_tr_b16 v[250:251], v205 offset:47680
	s_setprio 1
	s_waitcnt lgkmcnt(6)
	v_mfma_f32_32x32x16_bf16 v[32:47], v[210:213], v[92:95], v[32:47]
	s_setprio 0
	ds_read_b64_tr_b16 v[210:211], v205 offset:50240
	ds_read_b64_tr_b16 v[212:213], v205 offset:52800
	s_setprio 1
	s_waitcnt lgkmcnt(6)
	v_mfma_f32_32x32x16_bf16 v[16:31], v[224:227], v[80:83], v[16:31]
	s_setprio 0
	ds_read_b64_tr_b16 v[224:225], v205 offset:34944
	ds_read_b64_tr_b16 v[226:227], v205 offset:37504
	s_setprio 1
	s_waitcnt lgkmcnt(6)
	v_mfma_f32_32x32x16_bf16 v[16:31], v[228:231], v[84:87], v[16:31]
	s_setprio 0
	ds_read_b64_tr_b16 v[228:229], v205 offset:40064
	ds_read_b64_tr_b16 v[230:231], v205 offset:42624
	s_setprio 1
	s_waitcnt lgkmcnt(6)
	v_mfma_f32_32x32x16_bf16 v[16:31], v[248:251], v[88:91], v[16:31]
	s_setprio 0
	ds_read_b64_tr_b16 v[248:249], v205 offset:45184
	ds_read_b64_tr_b16 v[250:251], v205 offset:47744
	s_setprio 1
	s_waitcnt lgkmcnt(6)
	v_mfma_f32_32x32x16_bf16 v[16:31], v[210:213], v[92:95], v[16:31]
	s_setprio 0
	ds_read_b64_tr_b16 v[210:211], v205 offset:50304
	ds_read_b64_tr_b16 v[212:213], v205 offset:52864
	s_setprio 1
	s_waitcnt lgkmcnt(6)
	v_mfma_f32_32x32x16_bf16 v[0:15], v[224:227], v[80:83], v[0:15]
	s_setprio 0
	ds_read_b64_tr_b16 v[224:225], v205 offset:35008
	ds_read_b64_tr_b16 v[226:227], v205 offset:37568
	s_setprio 1
	s_waitcnt lgkmcnt(6)
	v_mfma_f32_32x32x16_bf16 v[0:15], v[228:231], v[84:87], v[0:15]
	s_setprio 0
	ds_read_b64_tr_b16 v[228:229], v205 offset:40128
	ds_read_b64_tr_b16 v[230:231], v205 offset:42688
	s_setprio 1
	s_waitcnt lgkmcnt(6)
	v_mfma_f32_32x32x16_bf16 v[0:15], v[248:251], v[88:91], v[0:15]
	s_setprio 0
	ds_read_b64_tr_b16 v[248:249], v205 offset:45248
	ds_read_b64_tr_b16 v[250:251], v205 offset:47808
	s_setprio 1
	s_waitcnt lgkmcnt(6)
	v_mfma_f32_32x32x16_bf16 v[0:15], v[210:213], v[92:95], v[0:15]
	s_setprio 0
	ds_read_b64_tr_b16 v[210:211], v205 offset:50368
	ds_read_b64_tr_b16 v[212:213], v205 offset:52928
	s_setprio 1
	s_waitcnt lgkmcnt(6)
	v_mfma_f32_32x32x16_bf16 v[48:63], v[224:227], v[80:83], v[48:63]
	s_setprio 0
	s_setprio 1
	s_waitcnt lgkmcnt(4)
	v_mfma_f32_32x32x16_bf16 v[48:63], v[228:231], v[84:87], v[48:63]
	s_setprio 0
	s_setprio 1
	s_waitcnt lgkmcnt(2)
	v_mfma_f32_32x32x16_bf16 v[48:63], v[248:251], v[88:91], v[48:63]
	s_setprio 0
	s_setprio 1
	s_waitcnt lgkmcnt(0)
	v_mfma_f32_32x32x16_bf16 v[48:63], v[210:213], v[92:95], v[48:63]
	s_setprio 0
	s_branch .LB2_end

.LkX_b0:
	s_mov_b32 m0, 0x24400
	s_nop 0
	global_load_lds_dwordx4 v132, s[80:81]
	s_branch .LXd_b0
.Lvo_b0:
	s_add_i32 m0, s32, 0xd800
	s_nop 0
	global_load_lds_dwordx4 v130, s[80:81]
	s_add_i32 m0, m0, 0x2000
	s_nop 0
	global_load_lds_dwordx4 v131, s[80:81]
	s_cmp_eq_u32 s56, 0
	s_cbranch_scc1 .Lvo2_b0
	s_add_i32 m0, s32, 0x11400
	s_nop 0
	global_load_lds_dwordx4 v132, s[80:81]

.Lwd_b0p:
	s_barrier
	s_mov_b32 s69, 0
	s_mul_i32 s4, s69, 0x5000
	v_add_u32_e32 v205, s4, v165
	ds_read_b64_tr_b16 v[224:225], v205 offset:34816
	ds_read_b64_tr_b16 v[226:227], v205 offset:37376
	ds_read_b64_tr_b16 v[228:229], v205 offset:39936
	ds_read_b64_tr_b16 v[230:231], v205 offset:42496
	ds_read_b64_tr_b16 v[248:249], v205 offset:45056
	ds_read_b64_tr_b16 v[250:251], v205 offset:47616
	ds_read_b64_tr_b16 v[210:211], v205 offset:50176
	ds_read_b64_tr_b16 v[212:213], v205 offset:52736
	s_setprio 1
	s_waitcnt lgkmcnt(6)
	v_mfma_f32_32x32x16_bf16 v[32:47], v[224:227], v[80:83], v[32:47]
	s_setprio 0
	ds_read_b64_tr_b16 v[224:225], v205 offset:34880
	ds_read_b64_tr_b16 v[226:227], v205 offset:37440
	s_setprio 1
	s_waitcnt lgkmcnt(6)
	v_mfma_f32_32x32x16_bf16 v[32:47], v[228:231], v[84:87], v[32:47]
	s_setprio 0
	ds_read_b64_tr_b16 v[228:229], v205 offset:40000
	ds_read_b64_tr_b16 v[230:231], v205 offset:42560
	s_setprio 1
	s_waitcnt lgkmcnt(6)
	v_mfma_f32_32x32x16_bf16 v[32:47], v[248:251], v[88:91], v[32:47]
	s_setprio 0
	ds_read_b64_tr_b16 v[248:249], v205 offset:45120
	ds_read_b64_tr_b16 v[250:251], v205 offset:47680
	s_setprio 1
	s_waitcnt lgkmcnt(6)
	v_mfma_f32_32x32x16_bf16 v[32:47], v[210:213], v[92:95], v[32:47]
	s_setprio 0
	ds_read_b64_tr_b16 v[210:211], v205 offset:50240
	ds_read_b64_tr_b16 v[212:213], v205 offset:52800
	s_setprio 1
	s_waitcnt lgkmcnt(6)
	v_mfma_f32_32x32x16_bf16 v[16:31], v[224:227], v[80:83], v[16:31]
	s_setprio 0
	ds_read_b64_tr_b16 v[224:225], v205 offset:34944
	ds_read_b64_tr_b16 v[226:227], v205 offset:37504
	s_setprio 1
	s_waitcnt lgkmcnt(6)
	v_mfma_f32_32x32x16_bf16 v[16:31], v[228:231], v[84:87], v[16:31]
	s_setprio 0
	ds_read_b64_tr_b16 v[228:229], v205 offset:40064
	ds_read_b64_tr_b16 v[230:231], v205 offset:42624
	s_setprio 1
	s_waitcnt lgkmcnt(6)
	v_mfma_f32_32x32x16_bf16 v[16:31], v[248:251], v[88:91], v[16:31]
	s_setprio 0
	ds_read_b64_tr_b16 v[248:249], v205 offset:45184
	ds_read_b64_tr_b16 v[250:251], v205 offset:47744
	s_setprio 1
	s_waitcnt lgkmcnt(6)
	v_mfma_f32_32x32x16_bf16 v[16:31], v[210:213], v[92:95], v[16:31]
	s_setprio 0
	ds_read_b64_tr_b16 v[210:211], v205 offset:50304
	ds_read_b64_tr_b16 v[212:213], v205 offset:52864
	s_setprio 1
	s_waitcnt lgkmcnt(6)
	v_mfma_f32_32x32x16_bf16 v[0:15], v[224:227], v[80:83], v[0:15]
	s_setprio 0
	ds_read_b64_tr_b16 v[224:225], v205 offset:35008
	ds_read_b64_tr_b16 v[226:227], v205 offset:37568
	s_setprio 1
	s_waitcnt lgkmcnt(6)
	v_mfma_f32_32x32x16_bf16 v[0:15], v[228:231], v[84:87], v[0:15]
	s_setprio 0
	ds_read_b64_tr_b16 v[228:229], v205 offset:40128
	ds_read_b64_tr_b16 v[230:231], v205 offset:42688
	s_setprio 1
	s_waitcnt lgkmcnt(6)
	v_mfma_f32_32x32x16_bf16 v[0:15], v[248:251], v[88:91], v[0:15]
	s_setprio 0
	ds_read_b64_tr_b16 v[248:249], v205 offset:45248
	ds_read_b64_tr_b16 v[250:251], v205 offset:47808
	s_setprio 1
	s_waitcnt lgkmcnt(6)
	v_mfma_f32_32x32x16_bf16 v[0:15], v[210:213], v[92:95], v[0:15]
	s_setprio 0
	ds_read_b64_tr_b16 v[210:211], v205 offset:50368
	ds_read_b64_tr_b16 v[212:213], v205 offset:52928
	s_setprio 1
	s_waitcnt lgkmcnt(6)
	v_mfma_f32_32x32x16_bf16 v[48:63], v[224:227], v[80:83], v[48:63]
	s_setprio 0
	s_setprio 1
	s_waitcnt lgkmcnt(4)
	v_mfma_f32_32x32x16_bf16 v[48:63], v[228:231], v[84:87], v[48:63]
	s_setprio 0
	s_setprio 1
	s_waitcnt lgkmcnt(2)
	v_mfma_f32_32x32x16_bf16 v[48:63], v[248:251], v[88:91], v[48:63]
	s_setprio 0
	s_setprio 1
	s_waitcnt lgkmcnt(0)
	v_mfma_f32_32x32x16_bf16 v[48:63], v[210:213], v[92:95], v[48:63]
	s_setprio 0
	s_branch .LB0_end

.Lba_a1:
	s_waitcnt lgkmcnt(0)
	v_add_u32_e32 v205, s68, v204
	v_add_u32_e32 v176, 0x17d00, v205
	v_add_u32_e32 v178, 0x17d80, v205
	ds_read2_b32 v[176:177], v176 offset1:1
	ds_read2_b32 v[178:179], v178 offset1:1
	v_add_u32_e32 v180, 0x17d08, v205
	v_add_u32_e32 v182, 0x17d88, v205
	v_add_u32_e32 v184, 0x17d20, v205
	v_add_u32_e32 v186, 0x17da0, v205
	v_add_u32_e32 v188, 0x17d28, v205
	v_add_u32_e32 v190, 0x17da8, v205
	v_add_u32_e32 v206, 0x17d40, v205
	v_add_u32_e32 v210, 0x17dc0, v205
	v_add_u32_e32 v212, 0x17d48, v205
	v_add_u32_e32 v221, 0x17dc8, v205
	ds_read2_b32 v[180:181], v180 offset1:1
	ds_read2_b32 v[182:183], v182 offset1:1
	ds_read2_b32 v[184:185], v184 offset1:1
	ds_read2_b32 v[186:187], v186 offset1:1
	ds_read2_b32 v[188:189], v188 offset1:1
	ds_read2_b32 v[190:191], v190 offset1:1
	ds_read2_b32 v[206:207], v206 offset1:1
	ds_read2_b32 v[210:211], v210 offset1:1
	ds_read2_b32 v[212:213], v212 offset1:1
	ds_read2_b32 v[224:225], v221 offset1:1
	v_add_u32_e32 v221, 0x17d60, v205
	v_add_u32_e32 v223, 0x17de0, v205
	ds_read2_b32 v[226:227], v221 offset1:1
	ds_read2_b32 v[228:229], v223 offset1:1
	v_add_u32_e32 v221, 0x17d68, v205
	v_add_u32_e32 v205, 0x17de8, v205
	ds_read2_b32 v[230:231], v221 offset1:1
	s_waitcnt lgkmcnt(14)
	v_pk_add_f32 v[96:97], v[96:97], v[176:177]
	ds_read2_b32 v[176:177], v205 offset1:1
	s_waitcnt lgkmcnt(3)
	v_pk_add_f32 v[108:109], v[108:109], v[226:227]
	v_pk_add_f32 v[106:107], v[106:107], v[212:213]
	s_waitcnt lgkmcnt(1)
	v_pk_add_f32 v[110:111], v[110:111], v[230:231]
	v_pk_add_f32 v[104:105], v[104:105], v[206:207]
	v_pk_add_f32 v[102:103], v[102:103], v[188:189]
	v_pk_add_f32 v[100:101], v[100:101], v[184:185]
	v_pk_add_f32 v[98:99], v[98:99], v[180:181]
	s_waitcnt lgkmcnt(0)
	v_pk_add_f32 v[94:95], v[94:95], v[176:177]
	v_pk_add_f32 v[92:93], v[92:93], v[228:229]
	v_pk_add_f32 v[90:91], v[90:91], v[224:225]
	v_pk_add_f32 v[88:89], v[88:89], v[210:211]
	v_pk_add_f32 v[86:87], v[86:87], v[190:191]
	v_pk_add_f32 v[84:85], v[84:85], v[186:187]
	v_pk_add_f32 v[82:83], v[82:83], v[182:183]
	v_pk_add_f32 v[80:81], v[80:81], v[178:179]
	s_nop 0
	s_branch .Latt_a1_stg

.Lw5_a1:
	s_waitcnt vmcnt(5) lgkmcnt(0)
	s_branch .Lwd_a1
.Lnodx_a1:
	s_nop 9
	s_branch .Lnod_a1
.LvX_a1:
	s_add_i32 m0, s32, 0xc400
	s_nop 0
	global_load_lds_dwordx4 v132, s[80:81]
	s_branch .LXd_a1
.Lvo_a1:
	s_add_i32 m0, s32, 0x8800
	s_nop 0
	global_load_lds_dwordx4 v130, s[80:81]
	s_add_i32 m0, m0, 0x2000
	s_nop 0
	global_load_lds_dwordx4 v131, s[80:81]
	s_cmp_eq_u32 s56, 4
	s_cbranch_scc0 .Lvo2_a1
	s_add_i32 m0, s32, 0xc400
	s_nop 0
	global_load_lds_dwordx4 v132, s[80:81]

.LvX_a2:
	s_add_i32 m0, s32, 0x11400
	s_nop 0
	global_load_lds_dwordx4 v132, s[80:81]
	s_branch .LXd_a2
.Lvo_a2:
	s_add_i32 m0, s32, 0xd800
	s_nop 0
	global_load_lds_dwordx4 v130, s[80:81]
	s_add_i32 m0, m0, 0x2000
	s_nop 0
	global_load_lds_dwordx4 v131, s[80:81]
	s_cmp_eq_u32 s56, 4
	s_cbranch_scc0 .Lvo2_a2
	s_add_i32 m0, s32, 0x11400
	s_nop 0
	global_load_lds_dwordx4 v132, s[80:81]

.LvX_a0:
	s_add_i32 m0, s32, 0x16400
	s_nop 0
	global_load_lds_dwordx4 v132, s[80:81]
	s_branch .LXd_a0
.Lvo_a0:
	s_add_i32 m0, s32, 0x12800
	s_nop 0
	global_load_lds_dwordx4 v130, s[80:81]
	s_add_i32 m0, m0, 0x2000
	s_nop 0
	global_load_lds_dwordx4 v131, s[80:81]
	s_cmp_eq_u32 s56, 4
	s_cbranch_scc0 .Lvo2_a0
	s_add_i32 m0, s32, 0x16400
	s_nop 0
	global_load_lds_dwordx4 v132, s[80:81]
